# v39 + qk-norm GEMM epilogue: the 4 q/k gain vectors loaded once instead of 32 serialized load+vmcnt(0) steps per tile
# speedup vs baseline: 1.0064x; 1.0064x over previous
.LBB0_371:
	s_cmp_lt_i32 s42, s1
	s_cselect_b64 s[14:15], -1, 0
	s_cmp_lt_i32 s42, s49
	s_cselect_b32 s1, s75, s61
	s_cselect_b32 s0, s74, s60
	v_lshlrev_b32_e32 v0, 4, v179
	s_cmp_ge_i32 s42, s73
	s_waitcnt lgkmcnt(0)
	v_pk_mul_f32 v[150:151], v[128:129], v[134:135]
	v_lshl_add_u64 v[130:131], s[0:1], 0, v[0:1]
	s_cselect_b64 s[0:1], -1, 0
	v_pk_mul_f32 v[152:153], v[126:127], v[132:133]
	v_pk_mul_f32 v[160:161], v[150:151], v[148:149] op_sel_hi:[1,0]
	v_pk_mul_f32 v[150:151], v[124:125], v[138:139]
	v_pk_mul_f32 v[154:155], v[122:123], v[136:137]
	s_or_b64 s[0:1], s[14:15], s[0:1]
	v_pk_mul_f32 v[158:159], v[152:153], v[148:149] op_sel_hi:[1,0]
	v_pk_mul_f32 v[152:153], v[150:151], v[148:149] op_sel_hi:[1,0]
	v_pk_mul_f32 v[150:151], v[154:155], v[148:149] op_sel_hi:[1,0]
	v_pk_mul_f32 v[154:155], v[120:121], v[142:143]
	v_pk_mul_f32 v[162:163], v[118:119], v[140:141]
	s_or_b64 s[6:7], s[68:69], s[0:1]
	v_pk_mul_f32 v[156:157], v[154:155], v[148:149] op_sel_hi:[1,0]
	v_pk_mul_f32 v[154:155], v[162:163], v[148:149] op_sel_hi:[1,0]
	v_pk_mul_f32 v[162:163], v[116:117], v[146:147]
	v_pk_mul_f32 v[164:165], v[114:115], v[144:145]
	v_pk_mul_f32 v[162:163], v[162:163], v[148:149] op_sel_hi:[1,0]
	v_pk_mul_f32 v[164:165], v[164:165], v[148:149] op_sel_hi:[1,0]
	s_and_b64 vcc, exec, s[6:7]
	s_cbranch_vccnz .LBB0_373
	v_mov_b32_e32 v168, v159
	v_mov_b32_e32 v169, v151
	v_mov_b32_e32 v148, v158
	v_mov_b32_e32 v149, v150
	v_pk_mul_f32 v[168:169], v[168:169], v[168:169]
	v_mov_b32_e32 v170, v165
	v_pk_fma_f32 v[148:149], v[148:149], v[148:149], v[168:169]
	v_mov_b32_e32 v168, v160
	v_mov_b32_e32 v169, v152
	v_pk_fma_f32 v[148:149], v[168:169], v[168:169], v[148:149]
	v_mov_b32_e32 v168, v161
	v_mov_b32_e32 v169, v153
	v_mov_b32_e32 v171, v155
	v_pk_fma_f32 v[148:149], v[168:169], v[168:169], v[148:149]
	v_mov_b32_e32 v168, v164
	v_mov_b32_e32 v169, v154
	v_pk_mul_f32 v[170:171], v[170:171], v[170:171]
	v_add_f32_e32 v0, v148, v149
	v_pk_fma_f32 v[168:169], v[168:169], v[168:169], v[170:171]
	v_mov_b32_e32 v170, v162
	v_mov_b32_e32 v171, v156
	v_pk_fma_f32 v[168:169], v[170:171], v[170:171], v[168:169]
	v_mov_b32_e32 v170, v163
	v_mov_b32_e32 v171, v157
	v_pk_fma_f32 v[168:169], v[170:171], v[170:171], v[168:169]
	v_xor_b32_e32 v148, 16, v242
	v_add_f32_e32 v0, v169, v0
	v_add_f32_e32 v0, v168, v0
	global_load_dwordx4 v[182:185], v[130:131], off
	global_load_dwordx4 v[186:189], v[130:131], off offset:64
	global_load_dwordx4 v[190:193], v[130:131], off offset:128
	global_load_dwordx4 v[194:197], v[130:131], off offset:192
	v_cmp_lt_i32_e32 vcc, v148, v252
	s_waitcnt vmcnt(0)
	v_pk_mul_f32 v[158:159], v[158:159], v[182:183]
	v_cndmask_b32_e32 v148, v242, v148, vcc
	v_lshlrev_b32_e32 v148, 2, v148
	ds_bpermute_b32 v148, v148, v0
	v_cmp_lt_i32_e32 vcc, v246, v252
	s_waitcnt lgkmcnt(0)
	v_add_f32_e32 v0, v0, v148
	v_cndmask_b32_e32 v148, v242, v246, vcc
	v_lshlrev_b32_e32 v148, 2, v148
	ds_bpermute_b32 v148, v148, v0
	s_waitcnt lgkmcnt(0)
	v_add_f32_e32 v0, v0, v148
	v_fmamk_f32 v0, v0, 0x3c800000, v244
	v_cmp_gt_f32_e32 vcc, s33, v0
	v_mul_f32_e32 v148, 0x4b800000, v0
	s_nop 0
	v_cndmask_b32_e32 v0, v0, v148, vcc
	v_rsq_f32_e32 v0, v0
	s_nop 0
	v_mul_f32_e32 v148, 0x45800000, v0
	v_cndmask_b32_e32 v0, v0, v148, vcc
	v_pk_mul_f32 v[148:149], v[160:161], v[184:185]
	v_pk_mul_f32 v[160:161], v[148:149], v[0:1] op_sel_hi:[1,0]
	v_pk_mul_f32 v[158:159], v[158:159], v[0:1] op_sel_hi:[1,0]
	v_pk_mul_f32 v[148:149], v[152:153], v[188:189]
	v_pk_mul_f32 v[150:151], v[150:151], v[186:187]
	v_pk_mul_f32 v[152:153], v[148:149], v[0:1] op_sel_hi:[1,0]
	v_pk_mul_f32 v[150:151], v[150:151], v[0:1] op_sel_hi:[1,0]
	v_pk_mul_f32 v[148:149], v[156:157], v[192:193]
	v_pk_mul_f32 v[154:155], v[154:155], v[190:191]
	v_pk_mul_f32 v[156:157], v[148:149], v[0:1] op_sel_hi:[1,0]
	v_pk_mul_f32 v[154:155], v[154:155], v[0:1] op_sel_hi:[1,0]
	v_pk_mul_f32 v[148:149], v[162:163], v[196:197]
	v_pk_mul_f32 v[164:165], v[164:165], v[194:195]
	v_pk_mul_f32 v[162:163], v[148:149], v[0:1] op_sel_hi:[1,0]
	v_pk_mul_f32 v[164:165], v[164:165], v[0:1] op_sel_hi:[1,0]

.LBB0_375:
	v_pk_mul_f32 v[150:151], v[112:113], v[134:135]
	v_pk_mul_f32 v[152:153], v[110:111], v[132:133]
	s_waitcnt lgkmcnt(0)
	v_pk_mul_f32 v[160:161], v[150:151], v[166:167] op_sel_hi:[1,0]
	v_pk_mul_f32 v[150:151], v[108:109], v[138:139]
	v_pk_mul_f32 v[162:163], v[102:103], v[140:141]
	v_pk_mul_f32 v[156:157], v[150:151], v[166:167] op_sel_hi:[1,0]
	v_pk_mul_f32 v[150:151], v[104:105], v[142:143]
	s_xor_b64 s[0:1], s[6:7], -1
	v_pk_mul_f32 v[158:159], v[152:153], v[166:167] op_sel_hi:[1,0]
	v_pk_mul_f32 v[152:153], v[106:107], v[136:137]
	v_pk_mul_f32 v[154:155], v[150:151], v[166:167] op_sel_hi:[1,0]
	v_pk_mul_f32 v[150:151], v[162:163], v[166:167] op_sel_hi:[1,0]
	v_pk_mul_f32 v[162:163], v[100:101], v[146:147]
	v_pk_mul_f32 v[164:165], v[98:99], v[144:145]
	v_cndmask_b32_e64 v149, 0, 1, s[0:1]
	v_pk_mul_f32 v[152:153], v[152:153], v[166:167] op_sel_hi:[1,0]
	v_pk_mul_f32 v[162:163], v[162:163], v[166:167] op_sel_hi:[1,0]
	v_cmp_ne_u32_e64 s[40:41], 1, v149
	s_andn2_b64 vcc, exec, s[0:1]
	v_pk_mul_f32 v[164:165], v[164:165], v[166:167] op_sel_hi:[1,0]
	s_cbranch_vccnz .LBB0_377
	v_mov_b32_e32 v172, v159
	v_mov_b32_e32 v173, v153
	v_mov_b32_e32 v170, v158
	v_mov_b32_e32 v171, v152
	v_pk_mul_f32 v[172:173], v[172:173], v[172:173]
	v_mov_b32_e32 v174, v165
	v_pk_fma_f32 v[170:171], v[170:171], v[170:171], v[172:173]
	v_mov_b32_e32 v172, v160
	v_mov_b32_e32 v173, v156
	v_pk_fma_f32 v[170:171], v[172:173], v[172:173], v[170:171]
	v_mov_b32_e32 v172, v161
	v_mov_b32_e32 v173, v157
	v_mov_b32_e32 v175, v151
	v_pk_fma_f32 v[170:171], v[172:173], v[172:173], v[170:171]
	v_mov_b32_e32 v172, v164
	v_mov_b32_e32 v173, v150
	v_pk_mul_f32 v[174:175], v[174:175], v[174:175]
	v_add_f32_e32 v149, v170, v171
	v_pk_fma_f32 v[172:173], v[172:173], v[172:173], v[174:175]
	v_mov_b32_e32 v174, v162
	v_mov_b32_e32 v175, v154
	v_pk_fma_f32 v[172:173], v[174:175], v[174:175], v[172:173]
	v_mov_b32_e32 v174, v163
	v_mov_b32_e32 v175, v155
	v_pk_fma_f32 v[172:173], v[174:175], v[174:175], v[172:173]
	v_xor_b32_e32 v166, 16, v242
	v_add_f32_e32 v149, v173, v149
	v_add_f32_e32 v149, v172, v149
	v_cmp_lt_i32_e32 vcc, v166, v252
	v_pk_mul_f32 v[160:161], v[160:161], v[184:185]
	v_pk_mul_f32 v[158:159], v[158:159], v[182:183]
	v_cndmask_b32_e32 v166, v242, v166, vcc
	v_lshlrev_b32_e32 v166, 2, v166
	ds_bpermute_b32 v166, v166, v149
	v_cmp_lt_i32_e32 vcc, v246, v252
	s_waitcnt lgkmcnt(0)
	v_add_f32_e32 v149, v149, v166
	v_cndmask_b32_e32 v166, v242, v246, vcc
	v_lshlrev_b32_e32 v166, 2, v166
	ds_bpermute_b32 v166, v166, v149
	s_waitcnt lgkmcnt(0)
	v_add_f32_e32 v149, v149, v166
	v_fmamk_f32 v149, v149, 0x3c800000, v244
	v_cmp_gt_f32_e32 vcc, s33, v149
	v_mul_f32_e32 v166, 0x4b800000, v149
	v_pk_mul_f32 v[156:157], v[156:157], v[188:189]
	v_pk_mul_f32 v[152:153], v[152:153], v[186:187]
	v_cndmask_b32_e32 v149, v149, v166, vcc
	v_rsq_f32_e32 v149, v149
	v_pk_mul_f32 v[154:155], v[154:155], v[192:193]
	v_pk_mul_f32 v[150:151], v[150:151], v[190:191]
	v_mul_f32_e32 v166, 0x45800000, v149
	v_cndmask_b32_e32 v166, v149, v166, vcc
	v_pk_mul_f32 v[160:161], v[160:161], v[166:167] op_sel_hi:[1,0]
	v_pk_mul_f32 v[158:159], v[158:159], v[166:167] op_sel_hi:[1,0]
	v_pk_mul_f32 v[156:157], v[156:157], v[166:167] op_sel_hi:[1,0]
	v_pk_mul_f32 v[152:153], v[152:153], v[166:167] op_sel_hi:[1,0]
	v_pk_mul_f32 v[154:155], v[154:155], v[166:167] op_sel_hi:[1,0]
	v_pk_mul_f32 v[150:151], v[150:151], v[166:167] op_sel_hi:[1,0]
	v_pk_mul_f32 v[162:163], v[162:163], v[196:197]
	v_pk_mul_f32 v[164:165], v[164:165], v[194:195]
	v_pk_mul_f32 v[162:163], v[162:163], v[166:167] op_sel_hi:[1,0]
	v_pk_mul_f32 v[164:165], v[164:165], v[166:167] op_sel_hi:[1,0]

.LBB0_379:
	v_pk_mul_f32 v[150:151], v[96:97], v[134:135]
	v_pk_mul_f32 v[152:153], v[94:95], v[132:133]
	s_waitcnt lgkmcnt(0)
	v_pk_mul_f32 v[160:161], v[150:151], v[164:165] op_sel_hi:[1,0]
	v_pk_mul_f32 v[150:151], v[92:93], v[138:139]
	v_pk_mul_f32 v[162:163], v[86:87], v[140:141]
	v_pk_mul_f32 v[156:157], v[150:151], v[164:165] op_sel_hi:[1,0]
	v_pk_mul_f32 v[150:151], v[88:89], v[142:143]
	v_pk_mul_f32 v[158:159], v[152:153], v[164:165] op_sel_hi:[1,0]
	v_pk_mul_f32 v[152:153], v[90:91], v[136:137]
	v_pk_mul_f32 v[154:155], v[150:151], v[164:165] op_sel_hi:[1,0]
	v_pk_mul_f32 v[150:151], v[162:163], v[164:165] op_sel_hi:[1,0]
	v_pk_mul_f32 v[162:163], v[84:85], v[146:147]
	v_pk_mul_f32 v[170:171], v[82:83], v[144:145]
	v_pk_mul_f32 v[152:153], v[152:153], v[164:165] op_sel_hi:[1,0]
	v_pk_mul_f32 v[162:163], v[162:163], v[164:165] op_sel_hi:[1,0]
	s_and_b64 vcc, exec, s[40:41]
	v_pk_mul_f32 v[164:165], v[170:171], v[164:165] op_sel_hi:[1,0]
	s_cbranch_vccnz .LBB0_381
	v_mov_b32_e32 v172, v159
	v_mov_b32_e32 v173, v153
	v_mov_b32_e32 v170, v158
	v_mov_b32_e32 v171, v152
	v_pk_mul_f32 v[172:173], v[172:173], v[172:173]
	v_mov_b32_e32 v174, v165
	v_pk_fma_f32 v[170:171], v[170:171], v[170:171], v[172:173]
	v_mov_b32_e32 v172, v160
	v_mov_b32_e32 v173, v156
	v_pk_fma_f32 v[170:171], v[172:173], v[172:173], v[170:171]
	v_mov_b32_e32 v172, v161
	v_mov_b32_e32 v173, v157
	v_mov_b32_e32 v175, v151
	v_pk_fma_f32 v[170:171], v[172:173], v[172:173], v[170:171]
	v_mov_b32_e32 v172, v164
	v_mov_b32_e32 v173, v150
	v_pk_mul_f32 v[174:175], v[174:175], v[174:175]
	v_add_f32_e32 v166, v170, v171
	v_pk_fma_f32 v[172:173], v[172:173], v[172:173], v[174:175]
	v_mov_b32_e32 v174, v162
	v_mov_b32_e32 v175, v154
	v_pk_fma_f32 v[172:173], v[174:175], v[174:175], v[172:173]
	v_mov_b32_e32 v174, v163
	v_mov_b32_e32 v175, v155
	v_pk_fma_f32 v[172:173], v[174:175], v[174:175], v[172:173]
	v_xor_b32_e32 v169, 16, v242
	v_add_f32_e32 v166, v173, v166
	v_add_f32_e32 v166, v172, v166
	v_cmp_lt_i32_e32 vcc, v169, v252
	v_pk_mul_f32 v[160:161], v[160:161], v[184:185]
	v_pk_mul_f32 v[158:159], v[158:159], v[182:183]
	v_cndmask_b32_e32 v169, v242, v169, vcc
	v_lshlrev_b32_e32 v169, 2, v169
	ds_bpermute_b32 v169, v169, v166
	v_cmp_lt_i32_e32 vcc, v246, v252
	s_waitcnt lgkmcnt(0)
	v_add_f32_e32 v166, v166, v169
	v_cndmask_b32_e32 v169, v242, v246, vcc
	v_lshlrev_b32_e32 v169, 2, v169
	ds_bpermute_b32 v169, v169, v166
	s_waitcnt lgkmcnt(0)
	v_add_f32_e32 v166, v166, v169
	v_fmamk_f32 v166, v166, 0x3c800000, v244
	v_cmp_gt_f32_e32 vcc, s33, v166
	v_mul_f32_e32 v169, 0x4b800000, v166
	v_pk_mul_f32 v[156:157], v[156:157], v[188:189]
	v_pk_mul_f32 v[152:153], v[152:153], v[186:187]
	v_cndmask_b32_e32 v166, v166, v169, vcc
	v_rsq_f32_e32 v166, v166
	v_pk_mul_f32 v[154:155], v[154:155], v[192:193]
	v_pk_mul_f32 v[150:151], v[150:151], v[190:191]
	v_mul_f32_e32 v169, 0x45800000, v166
	v_cndmask_b32_e32 v166, v166, v169, vcc
	v_pk_mul_f32 v[160:161], v[160:161], v[166:167] op_sel_hi:[1,0]
	v_pk_mul_f32 v[158:159], v[158:159], v[166:167] op_sel_hi:[1,0]
	v_pk_mul_f32 v[156:157], v[156:157], v[166:167] op_sel_hi:[1,0]
	v_pk_mul_f32 v[152:153], v[152:153], v[166:167] op_sel_hi:[1,0]
	v_pk_mul_f32 v[154:155], v[154:155], v[166:167] op_sel_hi:[1,0]
	v_pk_mul_f32 v[150:151], v[150:151], v[166:167] op_sel_hi:[1,0]
	v_pk_mul_f32 v[162:163], v[162:163], v[196:197]
	v_pk_mul_f32 v[164:165], v[164:165], v[194:195]
	v_pk_mul_f32 v[162:163], v[162:163], v[166:167] op_sel_hi:[1,0]
	v_pk_mul_f32 v[164:165], v[164:165], v[166:167] op_sel_hi:[1,0]

.LBB0_383:
	v_pk_mul_f32 v[150:151], v[80:81], v[134:135]
	v_pk_mul_f32 v[152:153], v[78:79], v[132:133]
	s_waitcnt lgkmcnt(0)
	v_pk_mul_f32 v[160:161], v[150:151], v[164:165] op_sel_hi:[1,0]
	v_pk_mul_f32 v[150:151], v[76:77], v[138:139]
	v_pk_mul_f32 v[162:163], v[70:71], v[140:141]
	v_pk_mul_f32 v[156:157], v[150:151], v[164:165] op_sel_hi:[1,0]
	v_pk_mul_f32 v[150:151], v[72:73], v[142:143]
	v_pk_mul_f32 v[158:159], v[152:153], v[164:165] op_sel_hi:[1,0]
	v_pk_mul_f32 v[152:153], v[74:75], v[136:137]
	v_pk_mul_f32 v[154:155], v[150:151], v[164:165] op_sel_hi:[1,0]
	v_pk_mul_f32 v[150:151], v[162:163], v[164:165] op_sel_hi:[1,0]
	v_pk_mul_f32 v[162:163], v[68:69], v[146:147]
	v_pk_mul_f32 v[170:171], v[66:67], v[144:145]
	v_pk_mul_f32 v[152:153], v[152:153], v[164:165] op_sel_hi:[1,0]
	v_pk_mul_f32 v[162:163], v[162:163], v[164:165] op_sel_hi:[1,0]
	s_and_b64 vcc, exec, s[40:41]
	v_pk_mul_f32 v[164:165], v[170:171], v[164:165] op_sel_hi:[1,0]
	s_cbranch_vccnz .LBB0_385
	v_mov_b32_e32 v172, v159
	v_mov_b32_e32 v173, v153
	v_mov_b32_e32 v170, v158
	v_mov_b32_e32 v171, v152
	v_pk_mul_f32 v[172:173], v[172:173], v[172:173]
	v_mov_b32_e32 v174, v165
	v_pk_fma_f32 v[170:171], v[170:171], v[170:171], v[172:173]
	v_mov_b32_e32 v172, v160
	v_mov_b32_e32 v173, v156
	v_pk_fma_f32 v[170:171], v[172:173], v[172:173], v[170:171]
	v_mov_b32_e32 v172, v161
	v_mov_b32_e32 v173, v157
	v_mov_b32_e32 v175, v151
	v_pk_fma_f32 v[170:171], v[172:173], v[172:173], v[170:171]
	v_mov_b32_e32 v172, v164
	v_mov_b32_e32 v173, v150
	v_pk_mul_f32 v[174:175], v[174:175], v[174:175]
	v_add_f32_e32 v166, v170, v171
	v_pk_fma_f32 v[172:173], v[172:173], v[172:173], v[174:175]
	v_mov_b32_e32 v174, v162
	v_mov_b32_e32 v175, v154
	v_pk_fma_f32 v[172:173], v[174:175], v[174:175], v[172:173]
	v_mov_b32_e32 v174, v163
	v_mov_b32_e32 v175, v155
	v_pk_fma_f32 v[172:173], v[174:175], v[174:175], v[172:173]
	v_xor_b32_e32 v169, 16, v242
	v_add_f32_e32 v166, v173, v166
	v_add_f32_e32 v166, v172, v166
	v_cmp_lt_i32_e32 vcc, v169, v252
	v_pk_mul_f32 v[160:161], v[160:161], v[184:185]
	v_pk_mul_f32 v[158:159], v[158:159], v[182:183]
	v_cndmask_b32_e32 v169, v242, v169, vcc
	v_lshlrev_b32_e32 v169, 2, v169
	ds_bpermute_b32 v169, v169, v166
	v_cmp_lt_i32_e32 vcc, v246, v252
	s_waitcnt lgkmcnt(0)
	v_add_f32_e32 v166, v166, v169
	v_cndmask_b32_e32 v169, v242, v246, vcc
	v_lshlrev_b32_e32 v169, 2, v169
	ds_bpermute_b32 v169, v169, v166
	s_waitcnt lgkmcnt(0)
	v_add_f32_e32 v166, v166, v169
	v_fmamk_f32 v166, v166, 0x3c800000, v244
	v_cmp_gt_f32_e32 vcc, s33, v166
	v_mul_f32_e32 v169, 0x4b800000, v166
	v_pk_mul_f32 v[156:157], v[156:157], v[188:189]
	v_pk_mul_f32 v[152:153], v[152:153], v[186:187]
	v_cndmask_b32_e32 v166, v166, v169, vcc
	v_rsq_f32_e32 v166, v166
	v_pk_mul_f32 v[154:155], v[154:155], v[192:193]
	v_pk_mul_f32 v[150:151], v[150:151], v[190:191]
	v_mul_f32_e32 v169, 0x45800000, v166
	v_cndmask_b32_e32 v166, v166, v169, vcc
	v_pk_mul_f32 v[160:161], v[160:161], v[166:167] op_sel_hi:[1,0]
	v_pk_mul_f32 v[158:159], v[158:159], v[166:167] op_sel_hi:[1,0]
	v_pk_mul_f32 v[156:157], v[156:157], v[166:167] op_sel_hi:[1,0]
	v_pk_mul_f32 v[152:153], v[152:153], v[166:167] op_sel_hi:[1,0]
	v_pk_mul_f32 v[154:155], v[154:155], v[166:167] op_sel_hi:[1,0]
	v_pk_mul_f32 v[150:151], v[150:151], v[166:167] op_sel_hi:[1,0]
	v_pk_mul_f32 v[162:163], v[162:163], v[196:197]
	v_pk_mul_f32 v[164:165], v[164:165], v[194:195]
	v_pk_mul_f32 v[162:163], v[162:163], v[166:167] op_sel_hi:[1,0]
	v_pk_mul_f32 v[164:165], v[164:165], v[166:167] op_sel_hi:[1,0]

.LBB0_387:
	v_pk_mul_f32 v[150:151], v[64:65], v[134:135]
	v_pk_mul_f32 v[152:153], v[62:63], v[132:133]
	s_waitcnt lgkmcnt(0)
	v_pk_mul_f32 v[160:161], v[150:151], v[164:165] op_sel_hi:[1,0]
	v_pk_mul_f32 v[150:151], v[60:61], v[138:139]
	v_pk_mul_f32 v[162:163], v[54:55], v[140:141]
	v_pk_mul_f32 v[156:157], v[150:151], v[164:165] op_sel_hi:[1,0]
	v_pk_mul_f32 v[150:151], v[56:57], v[142:143]
	v_pk_mul_f32 v[158:159], v[152:153], v[164:165] op_sel_hi:[1,0]
	v_pk_mul_f32 v[152:153], v[58:59], v[136:137]
	v_pk_mul_f32 v[154:155], v[150:151], v[164:165] op_sel_hi:[1,0]
	v_pk_mul_f32 v[150:151], v[162:163], v[164:165] op_sel_hi:[1,0]
	v_pk_mul_f32 v[162:163], v[52:53], v[146:147]
	v_pk_mul_f32 v[170:171], v[50:51], v[144:145]
	v_pk_mul_f32 v[152:153], v[152:153], v[164:165] op_sel_hi:[1,0]
	v_pk_mul_f32 v[162:163], v[162:163], v[164:165] op_sel_hi:[1,0]
	s_and_b64 vcc, exec, s[40:41]
	v_pk_mul_f32 v[164:165], v[170:171], v[164:165] op_sel_hi:[1,0]
	s_cbranch_vccnz .LBB0_389
	v_mov_b32_e32 v172, v159
	v_mov_b32_e32 v173, v153
	v_mov_b32_e32 v170, v158
	v_mov_b32_e32 v171, v152
	v_pk_mul_f32 v[172:173], v[172:173], v[172:173]
	v_mov_b32_e32 v174, v165
	v_pk_fma_f32 v[170:171], v[170:171], v[170:171], v[172:173]
	v_mov_b32_e32 v172, v160
	v_mov_b32_e32 v173, v156
	v_pk_fma_f32 v[170:171], v[172:173], v[172:173], v[170:171]
	v_mov_b32_e32 v172, v161
	v_mov_b32_e32 v173, v157
	v_mov_b32_e32 v175, v151
	v_pk_fma_f32 v[170:171], v[172:173], v[172:173], v[170:171]
	v_mov_b32_e32 v172, v164
	v_mov_b32_e32 v173, v150
	v_pk_mul_f32 v[174:175], v[174:175], v[174:175]
	v_add_f32_e32 v166, v170, v171
	v_pk_fma_f32 v[172:173], v[172:173], v[172:173], v[174:175]
	v_mov_b32_e32 v174, v162
	v_mov_b32_e32 v175, v154
	v_pk_fma_f32 v[172:173], v[174:175], v[174:175], v[172:173]
	v_mov_b32_e32 v174, v163
	v_mov_b32_e32 v175, v155
	v_pk_fma_f32 v[172:173], v[174:175], v[174:175], v[172:173]
	v_xor_b32_e32 v169, 16, v242
	v_add_f32_e32 v166, v173, v166
	v_add_f32_e32 v166, v172, v166
	v_cmp_lt_i32_e32 vcc, v169, v252
	v_pk_mul_f32 v[160:161], v[160:161], v[184:185]
	v_pk_mul_f32 v[158:159], v[158:159], v[182:183]
	v_cndmask_b32_e32 v169, v242, v169, vcc
	v_lshlrev_b32_e32 v169, 2, v169
	ds_bpermute_b32 v169, v169, v166
	v_cmp_lt_i32_e32 vcc, v246, v252
	s_waitcnt lgkmcnt(0)
	v_add_f32_e32 v166, v166, v169
	v_cndmask_b32_e32 v169, v242, v246, vcc
	v_lshlrev_b32_e32 v169, 2, v169
	ds_bpermute_b32 v169, v169, v166
	s_waitcnt lgkmcnt(0)
	v_add_f32_e32 v166, v166, v169
	v_fmamk_f32 v166, v166, 0x3c800000, v244
	v_cmp_gt_f32_e32 vcc, s33, v166
	v_mul_f32_e32 v169, 0x4b800000, v166
	v_pk_mul_f32 v[156:157], v[156:157], v[188:189]
	v_pk_mul_f32 v[152:153], v[152:153], v[186:187]
	v_cndmask_b32_e32 v166, v166, v169, vcc
	v_rsq_f32_e32 v166, v166
	v_pk_mul_f32 v[154:155], v[154:155], v[192:193]
	v_pk_mul_f32 v[150:151], v[150:151], v[190:191]
	v_mul_f32_e32 v169, 0x45800000, v166
	v_cndmask_b32_e32 v166, v166, v169, vcc
	v_pk_mul_f32 v[160:161], v[160:161], v[166:167] op_sel_hi:[1,0]
	v_pk_mul_f32 v[158:159], v[158:159], v[166:167] op_sel_hi:[1,0]
	v_pk_mul_f32 v[156:157], v[156:157], v[166:167] op_sel_hi:[1,0]
	v_pk_mul_f32 v[152:153], v[152:153], v[166:167] op_sel_hi:[1,0]
	v_pk_mul_f32 v[154:155], v[154:155], v[166:167] op_sel_hi:[1,0]
	v_pk_mul_f32 v[150:151], v[150:151], v[166:167] op_sel_hi:[1,0]
	v_pk_mul_f32 v[162:163], v[162:163], v[196:197]
	v_pk_mul_f32 v[164:165], v[164:165], v[194:195]
	v_pk_mul_f32 v[162:163], v[162:163], v[166:167] op_sel_hi:[1,0]
	v_pk_mul_f32 v[164:165], v[164:165], v[166:167] op_sel_hi:[1,0]

.LBB0_391:
	v_pk_mul_f32 v[150:151], v[48:49], v[134:135]
	v_pk_mul_f32 v[152:153], v[46:47], v[132:133]
	s_waitcnt lgkmcnt(0)
	v_pk_mul_f32 v[160:161], v[150:151], v[164:165] op_sel_hi:[1,0]
	v_pk_mul_f32 v[150:151], v[44:45], v[138:139]
	v_pk_mul_f32 v[162:163], v[38:39], v[140:141]
	v_pk_mul_f32 v[156:157], v[150:151], v[164:165] op_sel_hi:[1,0]
	v_pk_mul_f32 v[150:151], v[40:41], v[142:143]
	v_pk_mul_f32 v[158:159], v[152:153], v[164:165] op_sel_hi:[1,0]
	v_pk_mul_f32 v[152:153], v[42:43], v[136:137]
	v_pk_mul_f32 v[154:155], v[150:151], v[164:165] op_sel_hi:[1,0]
	v_pk_mul_f32 v[150:151], v[162:163], v[164:165] op_sel_hi:[1,0]
	v_pk_mul_f32 v[162:163], v[36:37], v[146:147]
	v_pk_mul_f32 v[170:171], v[34:35], v[144:145]
	v_pk_mul_f32 v[152:153], v[152:153], v[164:165] op_sel_hi:[1,0]
	v_pk_mul_f32 v[162:163], v[162:163], v[164:165] op_sel_hi:[1,0]
	s_and_b64 vcc, exec, s[40:41]
	v_pk_mul_f32 v[164:165], v[170:171], v[164:165] op_sel_hi:[1,0]
	s_cbranch_vccnz .LBB0_393
	v_mov_b32_e32 v172, v159
	v_mov_b32_e32 v173, v153
	v_mov_b32_e32 v170, v158
	v_mov_b32_e32 v171, v152
	v_pk_mul_f32 v[172:173], v[172:173], v[172:173]
	v_mov_b32_e32 v174, v165
	v_pk_fma_f32 v[170:171], v[170:171], v[170:171], v[172:173]
	v_mov_b32_e32 v172, v160
	v_mov_b32_e32 v173, v156
	v_pk_fma_f32 v[170:171], v[172:173], v[172:173], v[170:171]
	v_mov_b32_e32 v172, v161
	v_mov_b32_e32 v173, v157
	v_mov_b32_e32 v175, v151
	v_pk_fma_f32 v[170:171], v[172:173], v[172:173], v[170:171]
	v_mov_b32_e32 v172, v164
	v_mov_b32_e32 v173, v150
	v_pk_mul_f32 v[174:175], v[174:175], v[174:175]
	v_add_f32_e32 v166, v170, v171
	v_pk_fma_f32 v[172:173], v[172:173], v[172:173], v[174:175]
	v_mov_b32_e32 v174, v162
	v_mov_b32_e32 v175, v154
	v_pk_fma_f32 v[172:173], v[174:175], v[174:175], v[172:173]
	v_mov_b32_e32 v174, v163
	v_mov_b32_e32 v175, v155
	v_pk_fma_f32 v[172:173], v[174:175], v[174:175], v[172:173]
	v_xor_b32_e32 v169, 16, v242
	v_add_f32_e32 v166, v173, v166
	v_add_f32_e32 v166, v172, v166
	v_cmp_lt_i32_e32 vcc, v169, v252
	v_pk_mul_f32 v[160:161], v[160:161], v[184:185]
	v_pk_mul_f32 v[158:159], v[158:159], v[182:183]
	v_cndmask_b32_e32 v169, v242, v169, vcc
	v_lshlrev_b32_e32 v169, 2, v169
	ds_bpermute_b32 v169, v169, v166
	v_cmp_lt_i32_e32 vcc, v246, v252
	s_waitcnt lgkmcnt(0)
	v_add_f32_e32 v166, v166, v169
	v_cndmask_b32_e32 v169, v242, v246, vcc
	v_lshlrev_b32_e32 v169, 2, v169
	ds_bpermute_b32 v169, v169, v166
	s_waitcnt lgkmcnt(0)
	v_add_f32_e32 v166, v166, v169
	v_fmamk_f32 v166, v166, 0x3c800000, v244
	v_cmp_gt_f32_e32 vcc, s33, v166
	v_mul_f32_e32 v169, 0x4b800000, v166
	v_pk_mul_f32 v[156:157], v[156:157], v[188:189]
	v_pk_mul_f32 v[152:153], v[152:153], v[186:187]
	v_cndmask_b32_e32 v166, v166, v169, vcc
	v_rsq_f32_e32 v166, v166
	v_pk_mul_f32 v[154:155], v[154:155], v[192:193]
	v_pk_mul_f32 v[150:151], v[150:151], v[190:191]
	v_mul_f32_e32 v169, 0x45800000, v166
	v_cndmask_b32_e32 v166, v166, v169, vcc
	v_pk_mul_f32 v[160:161], v[160:161], v[166:167] op_sel_hi:[1,0]
	v_pk_mul_f32 v[158:159], v[158:159], v[166:167] op_sel_hi:[1,0]
	v_pk_mul_f32 v[156:157], v[156:157], v[166:167] op_sel_hi:[1,0]
	v_pk_mul_f32 v[152:153], v[152:153], v[166:167] op_sel_hi:[1,0]
	v_pk_mul_f32 v[154:155], v[154:155], v[166:167] op_sel_hi:[1,0]
	v_pk_mul_f32 v[150:151], v[150:151], v[166:167] op_sel_hi:[1,0]
	v_pk_mul_f32 v[162:163], v[162:163], v[196:197]
	v_pk_mul_f32 v[164:165], v[164:165], v[194:195]
	v_pk_mul_f32 v[162:163], v[162:163], v[166:167] op_sel_hi:[1,0]
	v_pk_mul_f32 v[164:165], v[164:165], v[166:167] op_sel_hi:[1,0]

.LBB0_395:
	v_pk_mul_f32 v[150:151], v[32:33], v[134:135]
	v_pk_mul_f32 v[152:153], v[30:31], v[132:133]
	s_waitcnt lgkmcnt(0)
	v_pk_mul_f32 v[160:161], v[150:151], v[164:165] op_sel_hi:[1,0]
	v_pk_mul_f32 v[150:151], v[28:29], v[138:139]
	v_pk_mul_f32 v[162:163], v[22:23], v[140:141]
	v_pk_mul_f32 v[156:157], v[150:151], v[164:165] op_sel_hi:[1,0]
	v_pk_mul_f32 v[150:151], v[24:25], v[142:143]
	v_pk_mul_f32 v[158:159], v[152:153], v[164:165] op_sel_hi:[1,0]
	v_pk_mul_f32 v[152:153], v[26:27], v[136:137]
	v_pk_mul_f32 v[154:155], v[150:151], v[164:165] op_sel_hi:[1,0]
	v_pk_mul_f32 v[150:151], v[162:163], v[164:165] op_sel_hi:[1,0]
	v_pk_mul_f32 v[162:163], v[20:21], v[146:147]
	v_pk_mul_f32 v[170:171], v[18:19], v[144:145]
	v_pk_mul_f32 v[152:153], v[152:153], v[164:165] op_sel_hi:[1,0]
	v_pk_mul_f32 v[162:163], v[162:163], v[164:165] op_sel_hi:[1,0]
	s_and_b64 vcc, exec, s[40:41]
	v_pk_mul_f32 v[164:165], v[170:171], v[164:165] op_sel_hi:[1,0]
	s_cbranch_vccnz .LBB0_397
	v_mov_b32_e32 v172, v159
	v_mov_b32_e32 v173, v153
	v_mov_b32_e32 v170, v158
	v_mov_b32_e32 v171, v152
	v_pk_mul_f32 v[172:173], v[172:173], v[172:173]
	v_mov_b32_e32 v174, v165
	v_pk_fma_f32 v[170:171], v[170:171], v[170:171], v[172:173]
	v_mov_b32_e32 v172, v160
	v_mov_b32_e32 v173, v156
	v_pk_fma_f32 v[170:171], v[172:173], v[172:173], v[170:171]
	v_mov_b32_e32 v172, v161
	v_mov_b32_e32 v173, v157
	v_mov_b32_e32 v175, v151
	v_pk_fma_f32 v[170:171], v[172:173], v[172:173], v[170:171]
	v_mov_b32_e32 v172, v164
	v_mov_b32_e32 v173, v150
	v_pk_mul_f32 v[174:175], v[174:175], v[174:175]
	v_add_f32_e32 v166, v170, v171
	v_pk_fma_f32 v[172:173], v[172:173], v[172:173], v[174:175]
	v_mov_b32_e32 v174, v162
	v_mov_b32_e32 v175, v154
	v_pk_fma_f32 v[172:173], v[174:175], v[174:175], v[172:173]
	v_mov_b32_e32 v174, v163
	v_mov_b32_e32 v175, v155
	v_pk_fma_f32 v[172:173], v[174:175], v[174:175], v[172:173]
	v_xor_b32_e32 v169, 16, v242
	v_add_f32_e32 v166, v173, v166
	v_add_f32_e32 v166, v172, v166
	v_cmp_lt_i32_e32 vcc, v169, v252
	v_pk_mul_f32 v[160:161], v[160:161], v[184:185]
	v_pk_mul_f32 v[158:159], v[158:159], v[182:183]
	v_cndmask_b32_e32 v169, v242, v169, vcc
	v_lshlrev_b32_e32 v169, 2, v169
	ds_bpermute_b32 v169, v169, v166
	v_cmp_lt_i32_e32 vcc, v246, v252
	s_waitcnt lgkmcnt(0)
	v_add_f32_e32 v166, v166, v169
	v_cndmask_b32_e32 v169, v242, v246, vcc
	v_lshlrev_b32_e32 v169, 2, v169
	ds_bpermute_b32 v169, v169, v166
	s_waitcnt lgkmcnt(0)
	v_add_f32_e32 v166, v166, v169
	v_fmamk_f32 v166, v166, 0x3c800000, v244
	v_cmp_gt_f32_e32 vcc, s33, v166
	v_mul_f32_e32 v169, 0x4b800000, v166
	v_pk_mul_f32 v[156:157], v[156:157], v[188:189]
	v_pk_mul_f32 v[152:153], v[152:153], v[186:187]
	v_cndmask_b32_e32 v166, v166, v169, vcc
	v_rsq_f32_e32 v166, v166
	v_pk_mul_f32 v[154:155], v[154:155], v[192:193]
	v_pk_mul_f32 v[150:151], v[150:151], v[190:191]
	v_mul_f32_e32 v169, 0x45800000, v166
	v_cndmask_b32_e32 v166, v166, v169, vcc
	v_pk_mul_f32 v[160:161], v[160:161], v[166:167] op_sel_hi:[1,0]
	v_pk_mul_f32 v[158:159], v[158:159], v[166:167] op_sel_hi:[1,0]
	v_pk_mul_f32 v[156:157], v[156:157], v[166:167] op_sel_hi:[1,0]
	v_pk_mul_f32 v[152:153], v[152:153], v[166:167] op_sel_hi:[1,0]
	v_pk_mul_f32 v[154:155], v[154:155], v[166:167] op_sel_hi:[1,0]
	v_pk_mul_f32 v[150:151], v[150:151], v[166:167] op_sel_hi:[1,0]
	v_pk_mul_f32 v[162:163], v[162:163], v[196:197]
	v_pk_mul_f32 v[164:165], v[164:165], v[194:195]
	v_pk_mul_f32 v[162:163], v[162:163], v[166:167] op_sel_hi:[1,0]
	v_pk_mul_f32 v[164:165], v[164:165], v[166:167] op_sel_hi:[1,0]

.LBB0_399:
	v_pk_mul_f32 v[132:133], v[14:15], v[132:133]
	v_pk_mul_f32 v[134:135], v[16:17], v[134:135]
	s_waitcnt lgkmcnt(0)
	v_pk_mul_f32 v[150:151], v[132:133], v[154:155] op_sel_hi:[1,0]
	v_pk_mul_f32 v[132:133], v[12:13], v[138:139]
	v_pk_mul_f32 v[140:141], v[6:7], v[140:141]
	v_pk_mul_f32 v[138:139], v[132:133], v[154:155] op_sel_hi:[1,0]
	v_pk_mul_f32 v[132:133], v[8:9], v[142:143]
	v_pk_mul_f32 v[152:153], v[134:135], v[154:155] op_sel_hi:[1,0]
	v_pk_mul_f32 v[134:135], v[10:11], v[136:137]
	v_pk_mul_f32 v[136:137], v[132:133], v[154:155] op_sel_hi:[1,0]
	v_pk_mul_f32 v[132:133], v[140:141], v[154:155] op_sel_hi:[1,0]
	v_pk_mul_f32 v[140:141], v[4:5], v[146:147]
	v_pk_mul_f32 v[142:143], v[2:3], v[144:145]
	v_pk_mul_f32 v[134:135], v[134:135], v[154:155] op_sel_hi:[1,0]
	v_pk_mul_f32 v[140:141], v[140:141], v[154:155] op_sel_hi:[1,0]
	s_and_b64 vcc, exec, s[40:41]
	v_pk_mul_f32 v[142:143], v[142:143], v[154:155] op_sel_hi:[1,0]
	s_cbranch_vccnz .LBB0_401
	v_mov_b32_e32 v146, v151
	v_mov_b32_e32 v147, v135
	v_mov_b32_e32 v144, v150
	v_mov_b32_e32 v145, v134
	v_pk_mul_f32 v[146:147], v[146:147], v[146:147]
	v_mov_b32_e32 v154, v143
	v_pk_fma_f32 v[144:145], v[144:145], v[144:145], v[146:147]
	v_mov_b32_e32 v146, v152
	v_mov_b32_e32 v147, v138
	v_pk_fma_f32 v[144:145], v[146:147], v[146:147], v[144:145]
	v_mov_b32_e32 v146, v153
	v_mov_b32_e32 v147, v139
	v_mov_b32_e32 v155, v133
	v_pk_fma_f32 v[144:145], v[146:147], v[146:147], v[144:145]
	v_mov_b32_e32 v146, v142
	v_mov_b32_e32 v147, v132
	v_pk_mul_f32 v[154:155], v[154:155], v[154:155]
	v_add_f32_e32 v144, v144, v145
	v_pk_fma_f32 v[146:147], v[146:147], v[146:147], v[154:155]
	v_mov_b32_e32 v154, v140
	v_mov_b32_e32 v155, v136
	v_pk_fma_f32 v[146:147], v[154:155], v[154:155], v[146:147]
	v_mov_b32_e32 v154, v141
	v_mov_b32_e32 v155, v137
	v_pk_fma_f32 v[146:147], v[154:155], v[154:155], v[146:147]
	v_add_f32_e32 v144, v147, v144
	v_add_f32_e32 v144, v146, v144
	v_xor_b32_e32 v145, 16, v242
	v_cmp_lt_i32_e32 vcc, v145, v252
	v_pk_mul_f32 v[146:147], v[152:153], v[184:185]
	v_pk_mul_f32 v[150:151], v[150:151], v[182:183]
	v_cndmask_b32_e32 v145, v242, v145, vcc
	v_lshlrev_b32_e32 v145, 2, v145
	ds_bpermute_b32 v145, v145, v144
	v_cmp_lt_i32_e32 vcc, v246, v252
	s_waitcnt lgkmcnt(0)
	v_add_f32_e32 v144, v144, v145
	v_cndmask_b32_e32 v145, v242, v246, vcc
	v_lshlrev_b32_e32 v145, 2, v145
	ds_bpermute_b32 v145, v145, v144
	s_waitcnt lgkmcnt(0)
	v_add_f32_e32 v144, v144, v145
	v_fmamk_f32 v144, v144, 0x3c800000, v244
	v_cmp_gt_f32_e32 vcc, s33, v144
	v_mul_f32_e32 v145, 0x4b800000, v144
	v_pk_mul_f32 v[138:139], v[138:139], v[188:189]
	v_pk_mul_f32 v[134:135], v[134:135], v[186:187]
	v_cndmask_b32_e32 v144, v144, v145, vcc
	v_rsq_f32_e32 v144, v144
	v_pk_mul_f32 v[136:137], v[136:137], v[192:193]
	v_pk_mul_f32 v[132:133], v[132:133], v[190:191]
	v_mul_f32_e32 v145, 0x45800000, v144
	v_cndmask_b32_e32 v144, v144, v145, vcc
	v_pk_mul_f32 v[152:153], v[146:147], v[144:145] op_sel_hi:[1,0]
	v_pk_mul_f32 v[150:151], v[150:151], v[144:145] op_sel_hi:[1,0]
	v_pk_mul_f32 v[138:139], v[138:139], v[144:145] op_sel_hi:[1,0]
	v_pk_mul_f32 v[134:135], v[134:135], v[144:145] op_sel_hi:[1,0]
	v_pk_mul_f32 v[136:137], v[136:137], v[144:145] op_sel_hi:[1,0]
	v_pk_mul_f32 v[132:133], v[132:133], v[144:145] op_sel_hi:[1,0]
	v_pk_mul_f32 v[130:131], v[140:141], v[196:197]
	v_pk_mul_f32 v[142:143], v[142:143], v[194:195]
	v_pk_mul_f32 v[140:141], v[130:131], v[144:145] op_sel_hi:[1,0]
	v_pk_mul_f32 v[142:143], v[142:143], v[144:145] op_sel_hi:[1,0]
